# phase-U unit order: three workgroup groups (A A A A X S | A A X S A A | X S A A A A) instead of two
# baseline (speedup 1.0000x reference)
; __global__ void __launch_bounds__(NTHR) mega_fwd(Params p) {
;     ...
;         if ((ph & 1) == 0) {
;             const int nkv = (l == 0) ? 256 : 0, nunits = 256 + nkv + 1024 + 256 + 256;
;             for (int u = bid; u < nunits; u += nb) {
;                 int v = u;
;                 if (v < 256) { unit_B1(p, lds, l, v); continue; }
;                 v -= 256;
;                 if (v < nkv) { unit_KV(p, lds, v >> 7, (v >> 2) & 31, v & 3); continue; }
;                 v -= nkv;
;                 if (v < 1024) { unit_A(p, lds, l, v & 255, v >> 8); continue; }
;                 v -= 1024;
;                 const int s = v & 255, xcd = s & 7, i = s >> 3;
;                 if (v < 256) unit_X(p, lds, l, xcd * 32 + i);
;                 else unit_S5(p, lds, l, xcd * 2 + (i >> 4), i & 15);
;             }
.LBB0_663:
	v_writelane_b32 v245, s2, 5
	s_bfe_u32 s0, s2, 0x50003
	s_mul_i32 s1, s0, 11
	s_lshr_b32 s1, s1, 5
	s_mul_i32 s1, s1, 3
	s_sub_u32 s0, s0, s1
	s_cmp_eq_u32 s0, 0
	s_cbranch_scc1 .Lperm_done
	s_cmp_eq_u32 s0, 1
	s_cbranch_scc0 .Lperm_g2
	s_mov_b32 s1, 0x54763210
	s_mov_b32 s3, 0x04365210
	s_branch .Lperm_sel
.Lperm_g2:
	s_mov_b32 s1, 0x54327610
	s_mov_b32 s3, 0x04321650
.Lperm_sel:
	s_cmp_lg_u32 s24, 0
	s_cselect_b32 s1, s1, s3
	s_lshr_b32 s0, s2, 8
	s_lshl_b32 s0, s0, 2
	s_lshr_b32 s1, s1, s0
	s_and_b32 s1, s1, 15
	s_and_b32 s2, s2, 0xff
	s_lshl_b32 s1, s1, 8
	s_or_b32 s2, s2, s1
